# merge gate hook: per-pair in-order vmcnt ladder instead of one vmcnt(0) behind each batch of 16 gate loads, so the rescale VALU work runs while the batch is still arriving
# baseline (speedup 1.0000x reference)
; #define GAS __attribute__((address_space(1)))
; DI float bflo(unsigned u) { return __uint_as_float(u << 16); }
; DI float bfhi(unsigned u) { return __uint_as_float(u & 0xffff0000u); }
; DI float fast_rcp(float x) { return __builtin_amdgcn_rcpf(x); }
;     __device__ __forceinline__ void hook(f32x4 (&acc)[2][2][4][2], const Unit& u, int k, int wr, int wc, int fr, int fq) const {
;     ...
;         for (int ai = 0; ai < 2; ++ai) {
;             u32x4 ga[4][2], gb[4][2];
; #pragma unroll
;             for (int m = 0; m < 4; ++m) { const bf16_t* gp = Gp + (size_t)(row0 + ai * HALF + m * 16) * GW + k * DM + col0;
; #pragma unroll
;                 for (int bj = 0; bj < 2; ++bj) { ga[m][bj] = *(const GAS u32x4*)(gp + bj * HALF); gb[m][bj] = *(const GAS u32x4*)(gp + DM + bj * HALF); } }
; #pragma unroll
;             for (int m = 0; m < 4; ++m)
; #pragma unroll
;                 for (int bj = 0; bj < 2; ++bj) { const u32x4 a = ga[m][bj], b = gb[m][bj];
;                     f32x4 r0, r1;
;                     r0[0] = bflo(a.x) * fast_rcp(bflo(b.x)); r0[1] = bfhi(a.x) * fast_rcp(bfhi(b.x)); r0[2] = bflo(a.y) * fast_rcp(bflo(b.y)); r0[3] = bfhi(a.y) * fast_rcp(bfhi(b.y));
;                     r1[0] = bflo(a.z) * fast_rcp(bflo(b.z)); r1[1] = bfhi(a.z) * fast_rcp(bfhi(b.z)); r1[2] = bflo(a.w) * fast_rcp(bflo(b.w)); r1[3] = bfhi(a.w) * fast_rcp(bfhi(b.w));
;                     acc[ai][bj][m][0] *= r0; acc[ai][bj][m][1] *= r1; }
.LBB0_264:
	s_cmp_eq_u32 s92, 0
	s_cselect_b64 s[34:35], -1, 0
	s_and_b32 s54, s5, 6
	s_cmp_lg_u32 s54, 0
	s_cselect_b64 s[54:55], -1, 0
	s_or_b64 s[34:35], s[34:35], s[54:55]
	s_and_b64 vcc, exec, s[34:35]
	s_cbranch_vccnz .LBB0_263
	v_mov_b32_e32 v2, v222
	v_mov_b32_e32 v132, v224
	s_add_u32 s34, s57, s92
	v_ashrrev_i32_e32 v133, 31, v132
	v_ashrrev_i32_e32 v3, 31, v2
	v_lshlrev_b64 v[132:133], 14, v[132:133]
	v_lshl_add_u64 v[2:3], v[2:3], 1, v[132:133]
	s_addc_u32 s35, s49, s93
	v_lshl_add_u64 v[2:3], s[34:35], 0, v[2:3]
	s_mov_b32 s34, 0x204ff000
	v_add_co_u32_e32 v132, vcc, s34, v2
	s_mov_b32 s34, 0x20500000
	s_nop 0
	v_addc_co_u32_e32 v133, vcc, 0, v3, vcc
	v_add_co_u32_e32 v134, vcc, s34, v2
	s_mov_b32 s34, 0x2053f000
	s_nop 0
	v_addc_co_u32_e32 v135, vcc, 0, v3, vcc
	global_load_dwordx4 v[188:191], v[134:135], off offset:-4096
	global_load_dwordx4 v[192:195], v[134:135], off
	global_load_dwordx4 v[180:183], v[132:133], off offset:256
	global_load_dwordx4 v[184:187], v[134:135], off offset:256
	v_add_co_u32_e32 v132, vcc, s34, v2
	s_mov_b32 s34, 0x20540000
	s_nop 0
	v_addc_co_u32_e32 v133, vcc, 0, v3, vcc
	v_add_co_u32_e32 v134, vcc, s34, v2
	s_mov_b32 s34, 0x2057f000
	s_nop 0
	v_addc_co_u32_e32 v135, vcc, 0, v3, vcc
	global_load_dwordx4 v[172:175], v[134:135], off offset:-4096
	global_load_dwordx4 v[176:179], v[134:135], off
	global_load_dwordx4 v[164:167], v[132:133], off offset:256
	global_load_dwordx4 v[168:171], v[134:135], off offset:256
	v_add_co_u32_e32 v132, vcc, s34, v2
	s_mov_b32 s34, 0x20580000
	s_nop 0
	v_addc_co_u32_e32 v133, vcc, 0, v3, vcc
	v_add_co_u32_e32 v134, vcc, s34, v2
	s_mov_b32 s34, 0x205bf000
	s_nop 0
	v_addc_co_u32_e32 v135, vcc, 0, v3, vcc
	global_load_dwordx4 v[156:159], v[134:135], off offset:-4096
	global_load_dwordx4 v[160:163], v[134:135], off
	global_load_dwordx4 v[136:139], v[132:133], off offset:256
	global_load_dwordx4 v[140:143], v[134:135], off offset:256
	v_add_co_u32_e32 v132, vcc, s34, v2
	s_mov_b32 s34, 0x205c0000
	s_nop 0
	v_addc_co_u32_e32 v133, vcc, 0, v3, vcc
	v_add_co_u32_e32 v144, vcc, s34, v2
	s_mov_b32 s34, 0x206ff000
	s_nop 0
	v_addc_co_u32_e32 v145, vcc, 0, v3, vcc
	global_load_dwordx4 v[148:151], v[144:145], off offset:-4096
	global_load_dwordx4 v[152:155], v[144:145], off
	s_nop 0
	global_load_dwordx4 v[132:135], v[132:133], off offset:256
	s_nop 0
	global_load_dwordx4 v[144:147], v[144:145], off offset:256
	s_waitcnt vmcnt(15)
	v_lshlrev_b32_e32 v242, 16, v188
	s_waitcnt vmcnt(14)
	v_lshlrev_b32_e32 v0, 16, v192
	v_rcp_f32_e32 v240, v0
	v_and_b32_e32 v0, 0xffff0000, v192
	v_rcp_f32_e32 v241, v0
	v_lshlrev_b32_e32 v0, 16, v193
	v_rcp_f32_e32 v192, v0
	v_and_b32_e32 v0, 0xffff0000, v193
	v_rcp_f32_e32 v193, v0
	v_and_b32_e32 v243, 0xffff0000, v188
	v_lshlrev_b32_e32 v188, 16, v189
	v_and_b32_e32 v189, 0xffff0000, v189
	v_lshlrev_b32_e32 v0, 16, v194
	v_pk_mul_f32 v[188:189], v[192:193], v[188:189]
	v_rcp_f32_e32 v192, v0
	v_and_b32_e32 v0, 0xffff0000, v194
	v_rcp_f32_e32 v193, v0
	v_lshlrev_b32_e32 v0, 16, v195
	v_rcp_f32_e32 v194, v0
	v_and_b32_e32 v0, 0xffff0000, v195
	v_rcp_f32_e32 v195, v0
	s_waitcnt vmcnt(12)
	v_lshlrev_b32_e32 v0, 16, v184
	v_pk_mul_f32 v[130:131], v[130:131], v[188:189]
	v_rcp_f32_e32 v188, v0
	v_and_b32_e32 v0, 0xffff0000, v184
	v_rcp_f32_e32 v189, v0
	v_lshlrev_b32_e32 v0, 16, v185
	v_rcp_f32_e32 v184, v0
	v_and_b32_e32 v0, 0xffff0000, v185
	v_rcp_f32_e32 v185, v0
	v_pk_mul_f32 v[240:241], v[240:241], v[242:243]
	v_lshlrev_b32_e32 v242, 16, v190
	v_and_b32_e32 v243, 0xffff0000, v190
	v_lshlrev_b32_e32 v190, 16, v191
	v_and_b32_e32 v191, 0xffff0000, v191
	v_pk_mul_f32 v[190:191], v[194:195], v[190:191]
	v_lshlrev_b32_e32 v0, 16, v186
	v_pk_mul_f32 v[126:127], v[126:127], v[190:191]
	v_lshlrev_b32_e32 v190, 16, v180
	v_and_b32_e32 v191, 0xffff0000, v180
	v_lshlrev_b32_e32 v180, 16, v181
	v_and_b32_e32 v181, 0xffff0000, v181
	v_pk_mul_f32 v[180:181], v[184:185], v[180:181]
	v_rcp_f32_e32 v184, v0
	v_and_b32_e32 v0, 0xffff0000, v186
	v_rcp_f32_e32 v185, v0
	v_lshlrev_b32_e32 v0, 16, v187
	v_rcp_f32_e32 v186, v0
	v_and_b32_e32 v0, 0xffff0000, v187
	v_rcp_f32_e32 v187, v0
	s_waitcnt vmcnt(10)
	v_lshlrev_b32_e32 v0, 16, v176
	v_pk_mul_f32 v[122:123], v[122:123], v[180:181]
	v_rcp_f32_e32 v180, v0
	v_and_b32_e32 v0, 0xffff0000, v176
	v_rcp_f32_e32 v181, v0
	v_lshlrev_b32_e32 v0, 16, v177
	v_rcp_f32_e32 v176, v0
	v_and_b32_e32 v0, 0xffff0000, v177
	v_rcp_f32_e32 v177, v0
	v_pk_mul_f32 v[188:189], v[188:189], v[190:191]
	v_lshlrev_b32_e32 v190, 16, v182
	v_and_b32_e32 v191, 0xffff0000, v182
	v_lshlrev_b32_e32 v182, 16, v183
	v_and_b32_e32 v183, 0xffff0000, v183
	v_pk_mul_f32 v[182:183], v[186:187], v[182:183]
	v_lshlrev_b32_e32 v0, 16, v178
	v_pk_mul_f32 v[118:119], v[118:119], v[182:183]
	v_lshlrev_b32_e32 v182, 16, v172
	v_and_b32_e32 v183, 0xffff0000, v172
	v_lshlrev_b32_e32 v172, 16, v173
	v_and_b32_e32 v173, 0xffff0000, v173
	v_pk_mul_f32 v[172:173], v[176:177], v[172:173]
	v_rcp_f32_e32 v176, v0
	v_and_b32_e32 v0, 0xffff0000, v178
	v_rcp_f32_e32 v177, v0
	v_lshlrev_b32_e32 v0, 16, v179
	v_rcp_f32_e32 v178, v0
	v_and_b32_e32 v0, 0xffff0000, v179
	v_rcp_f32_e32 v179, v0
	s_waitcnt vmcnt(8)
; DI float bflo(unsigned u) { return __uint_as_float(u << 16); }
; DI float bfhi(unsigned u) { return __uint_as_float(u & 0xffff0000u); }
; DI float fast_rcp(float x) { return __builtin_amdgcn_rcpf(x); }
;     __device__ __forceinline__ void hook(f32x4 (&acc)[2][2][4][2], const Unit& u, int k, int wr, int wc, int fr, int fq) const {
;     ...
;             for (int m = 0; m < 4; ++m)
; #pragma unroll
;                 for (int bj = 0; bj < 2; ++bj) { const u32x4 a = ga[m][bj], b = gb[m][bj];
;                     f32x4 r0, r1;
;                     r0[0] = bflo(a.x) * fast_rcp(bflo(b.x)); r0[1] = bfhi(a.x) * fast_rcp(bfhi(b.x)); r0[2] = bflo(a.y) * fast_rcp(bflo(b.y)); r0[3] = bfhi(a.y) * fast_rcp(bfhi(b.y));
;                     r1[0] = bflo(a.z) * fast_rcp(bflo(b.z)); r1[1] = bfhi(a.z) * fast_rcp(bfhi(b.z)); r1[2] = bflo(a.w) * fast_rcp(bflo(b.w)); r1[3] = bfhi(a.w) * fast_rcp(bfhi(b.w));
;                     acc[ai][bj][m][0] *= r0; acc[ai][bj][m][1] *= r1; }
	v_lshlrev_b32_e32 v0, 16, v168
	v_pk_mul_f32 v[114:115], v[114:115], v[172:173]
	v_rcp_f32_e32 v172, v0
	v_and_b32_e32 v0, 0xffff0000, v168
	v_rcp_f32_e32 v173, v0
	v_lshlrev_b32_e32 v0, 16, v169
	v_rcp_f32_e32 v168, v0
	v_and_b32_e32 v0, 0xffff0000, v169
	v_rcp_f32_e32 v169, v0
	v_pk_mul_f32 v[180:181], v[180:181], v[182:183]
	v_lshlrev_b32_e32 v182, 16, v174
	v_and_b32_e32 v183, 0xffff0000, v174
	v_lshlrev_b32_e32 v174, 16, v175
	v_and_b32_e32 v175, 0xffff0000, v175
	v_pk_mul_f32 v[174:175], v[178:179], v[174:175]
	v_lshlrev_b32_e32 v0, 16, v170
	v_pk_mul_f32 v[110:111], v[110:111], v[174:175]
	v_lshlrev_b32_e32 v174, 16, v164
	v_and_b32_e32 v175, 0xffff0000, v164
	v_lshlrev_b32_e32 v164, 16, v165
	v_and_b32_e32 v165, 0xffff0000, v165
	v_pk_mul_f32 v[164:165], v[168:169], v[164:165]
	v_rcp_f32_e32 v168, v0
	v_and_b32_e32 v0, 0xffff0000, v170
	v_rcp_f32_e32 v169, v0
	v_lshlrev_b32_e32 v0, 16, v171
	v_rcp_f32_e32 v170, v0
	v_and_b32_e32 v0, 0xffff0000, v171
	v_rcp_f32_e32 v171, v0
	s_waitcnt vmcnt(6)
	v_lshlrev_b32_e32 v0, 16, v160
	v_pk_mul_f32 v[106:107], v[106:107], v[164:165]
	v_rcp_f32_e32 v164, v0
	v_and_b32_e32 v0, 0xffff0000, v160
	v_rcp_f32_e32 v165, v0
	v_lshlrev_b32_e32 v0, 16, v161
	v_rcp_f32_e32 v160, v0
	v_and_b32_e32 v0, 0xffff0000, v161
	v_rcp_f32_e32 v161, v0
	v_pk_mul_f32 v[172:173], v[172:173], v[174:175]
	v_lshlrev_b32_e32 v174, 16, v166
	v_and_b32_e32 v175, 0xffff0000, v166
	v_lshlrev_b32_e32 v166, 16, v167
	v_and_b32_e32 v167, 0xffff0000, v167
	v_pk_mul_f32 v[166:167], v[170:171], v[166:167]
	v_lshlrev_b32_e32 v0, 16, v162
	v_pk_mul_f32 v[102:103], v[102:103], v[166:167]
	v_lshlrev_b32_e32 v166, 16, v156
	v_and_b32_e32 v167, 0xffff0000, v156
	v_lshlrev_b32_e32 v156, 16, v157
	v_and_b32_e32 v157, 0xffff0000, v157
	v_pk_mul_f32 v[156:157], v[160:161], v[156:157]
	v_rcp_f32_e32 v160, v0
	v_and_b32_e32 v0, 0xffff0000, v162
	v_rcp_f32_e32 v161, v0
	v_lshlrev_b32_e32 v0, 16, v163
	v_rcp_f32_e32 v162, v0
	v_and_b32_e32 v0, 0xffff0000, v163
	v_rcp_f32_e32 v163, v0
	s_waitcnt vmcnt(4)
	v_lshlrev_b32_e32 v0, 16, v140
	v_pk_mul_f32 v[98:99], v[98:99], v[156:157]
	v_rcp_f32_e32 v156, v0
	v_and_b32_e32 v0, 0xffff0000, v140
	v_rcp_f32_e32 v157, v0
	v_lshlrev_b32_e32 v0, 16, v141
	v_rcp_f32_e32 v140, v0
	v_and_b32_e32 v0, 0xffff0000, v141
	v_rcp_f32_e32 v141, v0
	v_pk_mul_f32 v[164:165], v[164:165], v[166:167]
	v_lshlrev_b32_e32 v166, 16, v158
	v_and_b32_e32 v167, 0xffff0000, v158
	v_lshlrev_b32_e32 v158, 16, v159
	v_and_b32_e32 v159, 0xffff0000, v159
	v_pk_mul_f32 v[158:159], v[162:163], v[158:159]
	v_lshlrev_b32_e32 v0, 16, v142
	v_pk_mul_f32 v[94:95], v[94:95], v[158:159]
	v_lshlrev_b32_e32 v158, 16, v136
	v_and_b32_e32 v159, 0xffff0000, v136
	v_lshlrev_b32_e32 v136, 16, v137
	v_and_b32_e32 v137, 0xffff0000, v137
	v_pk_mul_f32 v[136:137], v[140:141], v[136:137]
	v_rcp_f32_e32 v140, v0
	v_and_b32_e32 v0, 0xffff0000, v142
	v_rcp_f32_e32 v141, v0
	v_lshlrev_b32_e32 v0, 16, v143
	v_rcp_f32_e32 v142, v0
	v_and_b32_e32 v0, 0xffff0000, v143
	v_rcp_f32_e32 v143, v0
	s_waitcnt vmcnt(2)
	v_lshlrev_b32_e32 v0, 16, v152
	v_pk_mul_f32 v[90:91], v[90:91], v[136:137]
	v_rcp_f32_e32 v136, v0
	v_and_b32_e32 v0, 0xffff0000, v152
	v_rcp_f32_e32 v137, v0
	v_pk_mul_f32 v[156:157], v[156:157], v[158:159]
	v_lshlrev_b32_e32 v158, 16, v138
	v_and_b32_e32 v159, 0xffff0000, v138
	v_lshlrev_b32_e32 v138, 16, v139
	v_and_b32_e32 v139, 0xffff0000, v139
	v_pk_mul_f32 v[138:139], v[142:143], v[138:139]
	v_lshlrev_b32_e32 v0, 16, v153
	v_pk_mul_f32 v[86:87], v[86:87], v[138:139]
	v_lshlrev_b32_e32 v138, 16, v148
	v_and_b32_e32 v139, 0xffff0000, v148
	v_pk_mul_f32 v[136:137], v[136:137], v[138:139]
	v_rcp_f32_e32 v138, v0
	v_and_b32_e32 v0, 0xffff0000, v153
	v_rcp_f32_e32 v139, v0
	v_pk_mul_f32 v[140:141], v[140:141], v[158:159]
	v_lshlrev_b32_e32 v0, 16, v154
	v_pk_mul_f32 v[84:85], v[84:85], v[140:141]
	v_lshlrev_b32_e32 v140, 16, v149
	v_and_b32_e32 v141, 0xffff0000, v149
	v_pk_mul_f32 v[138:139], v[138:139], v[140:141]
	v_rcp_f32_e32 v140, v0
	v_and_b32_e32 v0, 0xffff0000, v154
	v_rcp_f32_e32 v141, v0
	v_lshlrev_b32_e32 v142, 16, v150
	v_and_b32_e32 v143, 0xffff0000, v150
	v_lshlrev_b32_e32 v0, 16, v155
	v_pk_mul_f32 v[140:141], v[140:141], v[142:143]
	v_rcp_f32_e32 v142, v0
	v_and_b32_e32 v0, 0xffff0000, v155
	v_rcp_f32_e32 v143, v0
	s_waitcnt vmcnt(0)
; #define GAS __attribute__((address_space(1)))
; DI float bflo(unsigned u) { return __uint_as_float(u << 16); }
; DI float bfhi(unsigned u) { return __uint_as_float(u & 0xffff0000u); }
; DI float fast_rcp(float x) { return __builtin_amdgcn_rcpf(x); }
;     __device__ __forceinline__ void hook(f32x4 (&acc)[2][2][4][2], const Unit& u, int k, int wr, int wc, int fr, int fq) const {
;     ...
;         for (int ai = 0; ai < 2; ++ai) {
;             u32x4 ga[4][2], gb[4][2];
; #pragma unroll
;             for (int m = 0; m < 4; ++m) { const bf16_t* gp = Gp + (size_t)(row0 + ai * HALF + m * 16) * GW + k * DM + col0;
; #pragma unroll
;                 for (int bj = 0; bj < 2; ++bj) { ga[m][bj] = *(const GAS u32x4*)(gp + bj * HALF); gb[m][bj] = *(const GAS u32x4*)(gp + DM + bj * HALF); } }
; #pragma unroll
;             for (int m = 0; m < 4; ++m)
; #pragma unroll
;                 for (int bj = 0; bj < 2; ++bj) { const u32x4 a = ga[m][bj], b = gb[m][bj];
;                     f32x4 r0, r1;
;                     r0[0] = bflo(a.x) * fast_rcp(bflo(b.x)); r0[1] = bfhi(a.x) * fast_rcp(bfhi(b.x)); r0[2] = bflo(a.y) * fast_rcp(bflo(b.y)); r0[3] = bfhi(a.y) * fast_rcp(bfhi(b.y));
;                     r1[0] = bflo(a.z) * fast_rcp(bflo(b.z)); r1[1] = bfhi(a.z) * fast_rcp(bfhi(b.z)); r1[2] = bflo(a.w) * fast_rcp(bflo(b.w)); r1[3] = bfhi(a.w) * fast_rcp(bfhi(b.w));
;                     acc[ai][bj][m][0] *= r0; acc[ai][bj][m][1] *= r1; }
	v_lshlrev_b32_e32 v0, 16, v144
	v_pk_mul_f32 v[80:81], v[80:81], v[136:137]
	v_rcp_f32_e32 v136, v0
	v_and_b32_e32 v0, 0xffff0000, v144
	v_rcp_f32_e32 v137, v0
	v_pk_mul_f32 v[82:83], v[82:83], v[138:139]
	v_lshlrev_b32_e32 v138, 16, v132
	v_and_b32_e32 v139, 0xffff0000, v132
	v_lshlrev_b32_e32 v0, 16, v145
	v_pk_mul_f32 v[136:137], v[136:137], v[138:139]
	v_rcp_f32_e32 v138, v0
	v_and_b32_e32 v0, 0xffff0000, v145
	v_rcp_f32_e32 v139, v0
	v_lshlrev_b32_e32 v132, 16, v133
	v_and_b32_e32 v133, 0xffff0000, v133
	v_lshlrev_b32_e32 v0, 16, v146
	v_pk_mul_f32 v[132:133], v[138:139], v[132:133]
	v_rcp_f32_e32 v138, v0
	v_and_b32_e32 v0, 0xffff0000, v146
	v_rcp_f32_e32 v139, v0
	v_pk_mul_f32 v[76:77], v[76:77], v[140:141]
	v_lshlrev_b32_e32 v140, 16, v134
	v_and_b32_e32 v141, 0xffff0000, v134
	v_lshlrev_b32_e32 v0, 16, v147
	v_pk_mul_f32 v[138:139], v[138:139], v[140:141]
	v_rcp_f32_e32 v140, v0
	v_and_b32_e32 v0, 0xffff0000, v147
	v_rcp_f32_e32 v141, v0
	v_lshlrev_b32_e32 v134, 16, v135
	v_and_b32_e32 v135, 0xffff0000, v135
	v_pk_mul_f32 v[74:75], v[74:75], v[132:133]
	v_add_co_u32_e32 v132, vcc, s34, v2
	v_pk_mul_f32 v[134:135], v[140:141], v[134:135]
	s_nop 0
	v_addc_co_u32_e32 v133, vcc, 0, v3, vcc
	s_mov_b32 s34, 0x20700000
	v_pk_mul_f32 v[70:71], v[70:71], v[134:135]
	v_add_co_u32_e32 v134, vcc, s34, v2
	v_pk_mul_f32 v[192:193], v[192:193], v[242:243]
	v_pk_mul_f32 v[176:177], v[176:177], v[182:183]
	v_addc_co_u32_e32 v135, vcc, 0, v3, vcc
	v_pk_mul_f32 v[124:125], v[124:125], v[192:193]
	v_pk_mul_f32 v[112:113], v[112:113], v[180:181]
	v_pk_mul_f32 v[108:109], v[108:109], v[176:177]
	v_pk_mul_f32 v[160:161], v[160:161], v[166:167]
	v_pk_mul_f32 v[96:97], v[96:97], v[164:165]
	global_load_dwordx4 v[176:179], v[134:135], off offset:-4096
	global_load_dwordx4 v[180:183], v[134:135], off
	global_load_dwordx4 v[164:167], v[132:133], off offset:256
	global_load_dwordx4 v[192:195], v[134:135], off offset:256
	s_mov_b32 s34, 0x2073f000
	v_add_co_u32_e32 v132, vcc, s34, v2
	s_mov_b32 s34, 0x20740000
	s_nop 0
	v_addc_co_u32_e32 v133, vcc, 0, v3, vcc
	v_add_co_u32_e32 v134, vcc, s34, v2
	v_pk_mul_f32 v[184:185], v[184:185], v[190:191]
	v_pk_mul_f32 v[168:169], v[168:169], v[174:175]
	v_addc_co_u32_e32 v135, vcc, 0, v3, vcc
	v_pk_mul_f32 v[120:121], v[120:121], v[188:189]
	v_pk_mul_f32 v[116:117], v[116:117], v[184:185]
	v_pk_mul_f32 v[104:105], v[104:105], v[172:173]
	v_pk_mul_f32 v[100:101], v[100:101], v[168:169]
	global_load_dwordx4 v[184:187], v[134:135], off offset:-4096
	global_load_dwordx4 v[188:191], v[134:135], off
	global_load_dwordx4 v[168:171], v[132:133], off offset:256
	global_load_dwordx4 v[172:175], v[134:135], off offset:256
	s_mov_b32 s34, 0x2077f000
	v_add_co_u32_e32 v132, vcc, s34, v2
	s_mov_b32 s34, 0x20780000
	s_nop 0
	v_addc_co_u32_e32 v133, vcc, 0, v3, vcc
	v_add_co_u32_e32 v134, vcc, s34, v2
	v_lshlrev_b32_e32 v148, 16, v151
	v_and_b32_e32 v149, 0xffff0000, v151
	v_addc_co_u32_e32 v135, vcc, 0, v3, vcc
	v_pk_mul_f32 v[92:93], v[92:93], v[160:161]
	v_pk_mul_f32 v[88:89], v[88:89], v[156:157]
	v_pk_mul_f32 v[142:143], v[142:143], v[148:149]
	global_load_dwordx4 v[156:159], v[134:135], off offset:-4096
	global_load_dwordx4 v[160:163], v[134:135], off
	global_load_dwordx4 v[148:151], v[132:133], off offset:256
	global_load_dwordx4 v[152:155], v[134:135], off offset:256
	s_mov_b32 s34, 0x207bf000
	v_add_co_u32_e32 v132, vcc, s34, v2
	s_mov_b32 s34, 0x207c0000
	s_nop 0
	v_addc_co_u32_e32 v133, vcc, 0, v3, vcc
	v_add_co_u32_e32 v2, vcc, s34, v2
	v_pk_mul_f32 v[78:79], v[78:79], v[142:143]
	s_nop 0
	v_addc_co_u32_e32 v3, vcc, 0, v3, vcc
	v_pk_mul_f32 v[72:73], v[72:73], v[136:137]
	v_pk_mul_f32 v[68:69], v[68:69], v[138:139]
	global_load_dwordx4 v[140:143], v[2:3], off offset:-4096
	global_load_dwordx4 v[144:147], v[2:3], off
	s_nop 0
	global_load_dwordx4 v[132:135], v[132:133], off offset:256
	s_nop 0
	global_load_dwordx4 v[136:139], v[2:3], off offset:256
	v_pk_mul_f32 v[128:129], v[128:129], v[240:241]
	s_waitcnt vmcnt(15)
	v_lshlrev_b32_e32 v240, 16, v176
	s_waitcnt vmcnt(14)
	v_lshlrev_b32_e32 v0, 16, v180
	v_rcp_f32_e32 v2, v0
	v_and_b32_e32 v0, 0xffff0000, v180
	v_rcp_f32_e32 v3, v0
	v_lshlrev_b32_e32 v0, 16, v181
	v_rcp_f32_e32 v180, v0
	v_and_b32_e32 v0, 0xffff0000, v181
	v_rcp_f32_e32 v181, v0
	v_and_b32_e32 v241, 0xffff0000, v176
	v_lshlrev_b32_e32 v176, 16, v177
	v_and_b32_e32 v177, 0xffff0000, v177
	v_lshlrev_b32_e32 v0, 16, v182
	v_pk_mul_f32 v[176:177], v[180:181], v[176:177]
	v_rcp_f32_e32 v180, v0
	v_and_b32_e32 v0, 0xffff0000, v182
	v_rcp_f32_e32 v181, v0
	v_lshlrev_b32_e32 v0, 16, v183
	v_rcp_f32_e32 v182, v0
	v_and_b32_e32 v0, 0xffff0000, v183
	v_pk_mul_f32 v[2:3], v[2:3], v[240:241]
	v_rcp_f32_e32 v183, v0
	s_waitcnt vmcnt(12)
	v_lshlrev_b32_e32 v0, 16, v192
	v_pk_mul_f32 v[64:65], v[64:65], v[2:3]
	v_rcp_f32_e32 v2, v0
	v_and_b32_e32 v0, 0xffff0000, v192
	v_rcp_f32_e32 v3, v0
	v_pk_mul_f32 v[66:67], v[66:67], v[176:177]
	v_lshlrev_b32_e32 v176, 16, v164
	v_and_b32_e32 v177, 0xffff0000, v164
	v_lshlrev_b32_e32 v0, 16, v193
	v_pk_mul_f32 v[2:3], v[2:3], v[176:177]
	v_rcp_f32_e32 v176, v0
	v_and_b32_e32 v0, 0xffff0000, v193
	v_rcp_f32_e32 v177, v0
	v_lshlrev_b32_e32 v164, 16, v165
	v_and_b32_e32 v165, 0xffff0000, v165
	v_lshlrev_b32_e32 v0, 16, v194
	v_pk_mul_f32 v[164:165], v[176:177], v[164:165]
	v_rcp_f32_e32 v176, v0
	v_and_b32_e32 v0, 0xffff0000, v194
	v_rcp_f32_e32 v177, v0
	v_lshlrev_b32_e32 v240, 16, v178
	v_and_b32_e32 v241, 0xffff0000, v178
	v_lshlrev_b32_e32 v178, 16, v179
	v_and_b32_e32 v179, 0xffff0000, v179
	v_pk_mul_f32 v[178:179], v[182:183], v[178:179]
	v_lshlrev_b32_e32 v0, 16, v195
	v_pk_mul_f32 v[62:63], v[62:63], v[178:179]
	v_lshlrev_b32_e32 v178, 16, v166
	v_and_b32_e32 v179, 0xffff0000, v166
	v_pk_mul_f32 v[176:177], v[176:177], v[178:179]
	v_rcp_f32_e32 v178, v0
	v_and_b32_e32 v0, 0xffff0000, v195
	v_rcp_f32_e32 v179, v0
	s_waitcnt vmcnt(10)
; DI float bflo(unsigned u) { return __uint_as_float(u << 16); }
; DI float bfhi(unsigned u) { return __uint_as_float(u & 0xffff0000u); }
; DI float fast_rcp(float x) { return __builtin_amdgcn_rcpf(x); }
;     __device__ __forceinline__ void hook(f32x4 (&acc)[2][2][4][2], const Unit& u, int k, int wr, int wc, int fr, int fq) const {
;     ...
;             for (int m = 0; m < 4; ++m)
; #pragma unroll
;                 for (int bj = 0; bj < 2; ++bj) { const u32x4 a = ga[m][bj], b = gb[m][bj];
;                     f32x4 r0, r1;
;                     r0[0] = bflo(a.x) * fast_rcp(bflo(b.x)); r0[1] = bfhi(a.x) * fast_rcp(bfhi(b.x)); r0[2] = bflo(a.y) * fast_rcp(bflo(b.y)); r0[3] = bfhi(a.y) * fast_rcp(bfhi(b.y));
;                     r1[0] = bflo(a.z) * fast_rcp(bflo(b.z)); r1[1] = bfhi(a.z) * fast_rcp(bfhi(b.z)); r1[2] = bflo(a.w) * fast_rcp(bflo(b.w)); r1[3] = bfhi(a.w) * fast_rcp(bfhi(b.w));
;                     acc[ai][bj][m][0] *= r0; acc[ai][bj][m][1] *= r1; }
	v_lshlrev_b32_e32 v0, 16, v188
	v_pk_mul_f32 v[56:57], v[56:57], v[2:3]
	v_rcp_f32_e32 v2, v0
	v_and_b32_e32 v0, 0xffff0000, v188
	v_rcp_f32_e32 v3, v0
	v_pk_mul_f32 v[58:59], v[58:59], v[164:165]
	v_lshlrev_b32_e32 v164, 16, v184
	v_and_b32_e32 v165, 0xffff0000, v184
	v_lshlrev_b32_e32 v0, 16, v189
	v_pk_mul_f32 v[2:3], v[2:3], v[164:165]
	v_rcp_f32_e32 v164, v0
	v_and_b32_e32 v0, 0xffff0000, v189
	v_rcp_f32_e32 v165, v0
	v_lshlrev_b32_e32 v166, 16, v167
	v_and_b32_e32 v167, 0xffff0000, v167
	v_pk_mul_f32 v[166:167], v[178:179], v[166:167]
	v_lshlrev_b32_e32 v0, 16, v190
	v_pk_mul_f32 v[54:55], v[54:55], v[166:167]
	v_lshlrev_b32_e32 v166, 16, v185
	v_and_b32_e32 v167, 0xffff0000, v185
	v_pk_mul_f32 v[164:165], v[164:165], v[166:167]
	v_rcp_f32_e32 v166, v0
	v_and_b32_e32 v0, 0xffff0000, v190
	v_rcp_f32_e32 v167, v0
	v_pk_mul_f32 v[52:53], v[52:53], v[176:177]
	v_lshlrev_b32_e32 v176, 16, v186
	v_and_b32_e32 v177, 0xffff0000, v186
	v_lshlrev_b32_e32 v0, 16, v191
	v_pk_mul_f32 v[166:167], v[166:167], v[176:177]
	v_rcp_f32_e32 v176, v0
	v_and_b32_e32 v0, 0xffff0000, v191
	v_rcp_f32_e32 v177, v0
	s_waitcnt vmcnt(8)
	v_lshlrev_b32_e32 v0, 16, v172
	v_pk_mul_f32 v[48:49], v[48:49], v[2:3]
	v_rcp_f32_e32 v2, v0
	v_and_b32_e32 v0, 0xffff0000, v172
	v_rcp_f32_e32 v3, v0
	v_pk_mul_f32 v[50:51], v[50:51], v[164:165]
	v_lshlrev_b32_e32 v164, 16, v168
	v_and_b32_e32 v165, 0xffff0000, v168
	v_lshlrev_b32_e32 v0, 16, v173
	v_pk_mul_f32 v[2:3], v[2:3], v[164:165]
	v_rcp_f32_e32 v164, v0
	v_and_b32_e32 v0, 0xffff0000, v173
	v_rcp_f32_e32 v165, v0
	v_pk_mul_f32 v[44:45], v[44:45], v[166:167]
	v_lshlrev_b32_e32 v166, 16, v169
	v_and_b32_e32 v167, 0xffff0000, v169
	v_lshlrev_b32_e32 v0, 16, v174
	v_pk_mul_f32 v[164:165], v[164:165], v[166:167]
	v_rcp_f32_e32 v166, v0
	v_and_b32_e32 v0, 0xffff0000, v174
	v_rcp_f32_e32 v167, v0
	v_lshlrev_b32_e32 v168, 16, v170
	v_and_b32_e32 v169, 0xffff0000, v170
	v_lshlrev_b32_e32 v0, 16, v175
	v_pk_mul_f32 v[166:167], v[166:167], v[168:169]
	v_rcp_f32_e32 v168, v0
	v_and_b32_e32 v0, 0xffff0000, v175
	v_rcp_f32_e32 v169, v0
	s_waitcnt vmcnt(6)
	v_lshlrev_b32_e32 v0, 16, v160
	v_pk_mul_f32 v[40:41], v[40:41], v[2:3]
	v_rcp_f32_e32 v2, v0
	v_and_b32_e32 v0, 0xffff0000, v160
	v_rcp_f32_e32 v3, v0
	v_lshlrev_b32_e32 v0, 16, v161
	v_rcp_f32_e32 v160, v0
	v_and_b32_e32 v0, 0xffff0000, v161
	v_rcp_f32_e32 v161, v0
	v_pk_mul_f32 v[42:43], v[42:43], v[164:165]
	v_lshlrev_b32_e32 v164, 16, v156
	v_and_b32_e32 v165, 0xffff0000, v156
	v_lshlrev_b32_e32 v156, 16, v157
	v_and_b32_e32 v157, 0xffff0000, v157
	v_lshlrev_b32_e32 v0, 16, v162
	v_pk_mul_f32 v[156:157], v[160:161], v[156:157]
	v_rcp_f32_e32 v160, v0
	v_and_b32_e32 v0, 0xffff0000, v162
	v_rcp_f32_e32 v161, v0
	v_lshlrev_b32_e32 v0, 16, v163
	v_rcp_f32_e32 v162, v0
	v_and_b32_e32 v0, 0xffff0000, v163
	v_pk_mul_f32 v[2:3], v[2:3], v[164:165]
	v_rcp_f32_e32 v163, v0
	s_waitcnt vmcnt(4)
	v_lshlrev_b32_e32 v0, 16, v152
	v_pk_mul_f32 v[32:33], v[32:33], v[2:3]
	v_rcp_f32_e32 v2, v0
	v_and_b32_e32 v0, 0xffff0000, v152
	v_rcp_f32_e32 v3, v0
	v_lshlrev_b32_e32 v0, 16, v153
	v_rcp_f32_e32 v152, v0
	v_and_b32_e32 v0, 0xffff0000, v153
	v_rcp_f32_e32 v153, v0
	v_pk_mul_f32 v[34:35], v[34:35], v[156:157]
	v_lshlrev_b32_e32 v156, 16, v148
	v_and_b32_e32 v157, 0xffff0000, v148
	v_lshlrev_b32_e32 v148, 16, v149
	v_and_b32_e32 v149, 0xffff0000, v149
	v_lshlrev_b32_e32 v0, 16, v154
	v_pk_mul_f32 v[148:149], v[152:153], v[148:149]
	v_rcp_f32_e32 v152, v0
	v_and_b32_e32 v0, 0xffff0000, v154
	v_rcp_f32_e32 v153, v0
	v_lshlrev_b32_e32 v0, 16, v155
	v_rcp_f32_e32 v154, v0
	v_and_b32_e32 v0, 0xffff0000, v155
	v_pk_mul_f32 v[2:3], v[2:3], v[156:157]
	v_rcp_f32_e32 v155, v0
	s_waitcnt vmcnt(2)
; DI float bflo(unsigned u) { return __uint_as_float(u << 16); }
; DI float bfhi(unsigned u) { return __uint_as_float(u & 0xffff0000u); }
; DI float fast_rcp(float x) { return __builtin_amdgcn_rcpf(x); }
;     __device__ __forceinline__ void hook(f32x4 (&acc)[2][2][4][2], const Unit& u, int k, int wr, int wc, int fr, int fq) const {
;     ...
;             for (int m = 0; m < 4; ++m)
; #pragma unroll
;                 for (int bj = 0; bj < 2; ++bj) { const u32x4 a = ga[m][bj], b = gb[m][bj];
;                     f32x4 r0, r1;
;                     r0[0] = bflo(a.x) * fast_rcp(bflo(b.x)); r0[1] = bfhi(a.x) * fast_rcp(bfhi(b.x)); r0[2] = bflo(a.y) * fast_rcp(bflo(b.y)); r0[3] = bfhi(a.y) * fast_rcp(bfhi(b.y));
;                     r1[0] = bflo(a.z) * fast_rcp(bflo(b.z)); r1[1] = bfhi(a.z) * fast_rcp(bfhi(b.z)); r1[2] = bflo(a.w) * fast_rcp(bflo(b.w)); r1[3] = bfhi(a.w) * fast_rcp(bfhi(b.w));
;                     acc[ai][bj][m][0] *= r0; acc[ai][bj][m][1] *= r1; }
;             asm volatile("" ::: "memory");
;         }
	v_lshlrev_b32_e32 v0, 16, v144
	v_pk_mul_f32 v[24:25], v[24:25], v[2:3]
	v_rcp_f32_e32 v2, v0
	v_and_b32_e32 v0, 0xffff0000, v144
	v_rcp_f32_e32 v3, v0
	v_lshlrev_b32_e32 v0, 16, v145
	v_rcp_f32_e32 v144, v0
	v_and_b32_e32 v0, 0xffff0000, v145
	v_rcp_f32_e32 v145, v0
	v_pk_mul_f32 v[26:27], v[26:27], v[148:149]
	v_lshlrev_b32_e32 v148, 16, v140
	v_and_b32_e32 v149, 0xffff0000, v140
	v_lshlrev_b32_e32 v140, 16, v141
	v_and_b32_e32 v141, 0xffff0000, v141
	v_lshlrev_b32_e32 v0, 16, v146
	v_pk_mul_f32 v[140:141], v[144:145], v[140:141]
	v_rcp_f32_e32 v144, v0
	v_and_b32_e32 v0, 0xffff0000, v146
	v_rcp_f32_e32 v145, v0
	v_lshlrev_b32_e32 v0, 16, v147
	v_rcp_f32_e32 v146, v0
	v_and_b32_e32 v0, 0xffff0000, v147
	v_pk_mul_f32 v[2:3], v[2:3], v[148:149]
	v_rcp_f32_e32 v147, v0
	s_waitcnt vmcnt(0)
	v_lshlrev_b32_e32 v0, 16, v136
	v_pk_mul_f32 v[16:17], v[16:17], v[2:3]
	v_rcp_f32_e32 v2, v0
	v_and_b32_e32 v0, 0xffff0000, v136
	v_rcp_f32_e32 v3, v0
	v_lshlrev_b32_e32 v0, 16, v137
	v_rcp_f32_e32 v136, v0
	v_and_b32_e32 v0, 0xffff0000, v137
	v_rcp_f32_e32 v137, v0
	v_pk_mul_f32 v[18:19], v[18:19], v[140:141]
	v_lshlrev_b32_e32 v140, 16, v132
	v_and_b32_e32 v141, 0xffff0000, v132
	v_lshlrev_b32_e32 v132, 16, v133
	v_and_b32_e32 v133, 0xffff0000, v133
	v_lshlrev_b32_e32 v0, 16, v138
	v_pk_mul_f32 v[132:133], v[136:137], v[132:133]
	v_rcp_f32_e32 v136, v0
	v_and_b32_e32 v0, 0xffff0000, v138
	v_rcp_f32_e32 v137, v0
	v_lshlrev_b32_e32 v0, 16, v139
	v_rcp_f32_e32 v138, v0
	v_and_b32_e32 v0, 0xffff0000, v139
	v_rcp_f32_e32 v139, v0
	v_lshlrev_b32_e32 v178, 16, v187
	v_and_b32_e32 v179, 0xffff0000, v187
	v_lshlrev_b32_e32 v170, 16, v171
	v_and_b32_e32 v171, 0xffff0000, v171
	v_lshlrev_b32_e32 v164, 16, v158
	v_and_b32_e32 v165, 0xffff0000, v158
	v_lshlrev_b32_e32 v158, 16, v159
	v_and_b32_e32 v159, 0xffff0000, v159
	v_lshlrev_b32_e32 v156, 16, v150
	v_and_b32_e32 v157, 0xffff0000, v150
	v_lshlrev_b32_e32 v150, 16, v151
	v_and_b32_e32 v151, 0xffff0000, v151
	v_lshlrev_b32_e32 v148, 16, v142
	v_and_b32_e32 v149, 0xffff0000, v142
	v_lshlrev_b32_e32 v142, 16, v143
	v_and_b32_e32 v143, 0xffff0000, v143
	v_pk_mul_f32 v[2:3], v[2:3], v[140:141]
	v_lshlrev_b32_e32 v140, 16, v134
	v_and_b32_e32 v141, 0xffff0000, v134
	v_lshlrev_b32_e32 v134, 16, v135
	v_and_b32_e32 v135, 0xffff0000, v135
	v_pk_mul_f32 v[180:181], v[180:181], v[240:241]
	v_pk_mul_f32 v[176:177], v[176:177], v[178:179]
	v_pk_mul_f32 v[168:169], v[168:169], v[170:171]
	v_pk_mul_f32 v[160:161], v[160:161], v[164:165]
	v_pk_mul_f32 v[158:159], v[162:163], v[158:159]
	v_pk_mul_f32 v[152:153], v[152:153], v[156:157]
	v_pk_mul_f32 v[150:151], v[154:155], v[150:151]
	v_pk_mul_f32 v[144:145], v[144:145], v[148:149]
	v_pk_mul_f32 v[142:143], v[146:147], v[142:143]
	v_pk_mul_f32 v[136:137], v[136:137], v[140:141]
	v_pk_mul_f32 v[134:135], v[138:139], v[134:135]
	v_pk_mul_f32 v[60:61], v[60:61], v[180:181]
	v_pk_mul_f32 v[46:47], v[46:47], v[176:177]
	v_pk_mul_f32 v[38:39], v[38:39], v[168:169]
	v_pk_mul_f32 v[36:37], v[36:37], v[166:167]
	v_pk_mul_f32 v[30:31], v[30:31], v[158:159]
	v_pk_mul_f32 v[28:29], v[28:29], v[160:161]
	v_pk_mul_f32 v[22:23], v[22:23], v[150:151]
	v_pk_mul_f32 v[20:21], v[20:21], v[152:153]
	v_pk_mul_f32 v[14:15], v[14:15], v[142:143]
	v_pk_mul_f32 v[12:13], v[12:13], v[144:145]
	v_pk_mul_f32 v[10:11], v[10:11], v[132:133]
	v_pk_mul_f32 v[8:9], v[8:9], v[2:3]
	v_pk_mul_f32 v[6:7], v[6:7], v[134:135]
	v_pk_mul_f32 v[4:5], v[4:5], v[136:137]
	s_branch .LBB0_263
